# P5 work queue in longest-first order: static first tickets are the longest prompt items, sample-row items are served between query blocks 4 and 3; on top of the stacked version
# baseline (speedup 1.0000x reference)
; __global__ void __launch_bounds__(512, 2) mega(Params P) {
;     ...
;                 if (tid == 0) *sitem = (int)atomicAdd(WSP(unsigned, WS_CTL) + 3600 + l + 2 * rep, 1u);
;                 __syncthreads();
;                 const int it = *sitem;
;                 if (it >= 1280) break;
;                 int type, b, hh, qb = 0, samp = 0, grp = 0;
;     ...
;                 if (it < 256) { type = 0; grp = 7 - (it >> 5); b = (it >> 2) & 7; hh = it & 3; }
;     ...
;                 if (it < 256) { if (it >= 32) continue; type = 0; grp = 7; b = (it >> 2) & 7; hh = it & 3; }
;     ...
;                 else if (it < 384) { type = 1; samp = 1; b = (it - 256) >> 3; hh = it & 7; }
;                 else if (it < 448) { type = 2; samp = 1; b = (it - 384) >> 2; hh = it & 3; }
;                 else if (it < 512) { type = 0; samp = 1; b = (it - 448) >> 2; hh = it & 3; }
;                 else { const int q = it - 512, s = q % 96; qb = 7 - q / 96; if (s < 64) { type = 1; b = s >> 3; hh = s & 7; } else { type = 2; b = (s - 64) >> 2; hh = s & 3; } }
.LBB0_889:
	s_mov_b32 s0, s21
	v_mbcnt_lo_u32_b32 v0, -1, 0
	v_mbcnt_hi_u32_b32 v0, -1, v0
	s_nop 0
	v_lshl_add_u32 v148, s0, 6, v0
	s_mov_b32 s0, s97
	v_cmp_eq_u32_e32 vcc, 0, v148
	v_readlane_b32 s0, v254, 19
	v_readlane_b32 s4, v254, 23
	v_readlane_b32 s5, v254, 24
	v_readlane_b32 s6, v254, 25
	v_readlane_b32 s7, v254, 26
	v_readlane_b32 s1, v254, 20
	s_mov_b64 s[52:53], s[6:7]
	s_mov_b64 s[16:17], s[4:5]
	v_readlane_b32 s2, v254, 21
	v_readlane_b32 s3, v254, 22
	s_barrier
	s_and_saveexec_b64 s[0:1], vcc
	s_cbranch_execz .LBB0_893
	s_cmp_eq_u32 s98, 0
	s_cbranch_scc1 .Ldq_dyn
	s_mov_b32 s98, 0
	s_add_i32 s2, s97, 0x1e0
	s_cmp_lt_u32 s97, 32
	s_cselect_b32 s2, s97, s2
	s_branch .Ldq_pub

; __global__ void __launch_bounds__(512, 2) mega(Params P) {
;     ...
;                 if (tid == 0) *sitem = (int)atomicAdd(WSP(unsigned, WS_CTL) + 3600 + l + 2 * rep, 1u);
;                 __syncthreads();
;                 const int it = *sitem;
;                 if (it >= 1280) break;
;                 int type, b, hh, qb = 0, samp = 0, grp = 0;
;     ...
;                 if (it < 256) { type = 0; grp = 7 - (it >> 5); b = (it >> 2) & 7; hh = it & 3; }
;     ...
;                 if (it < 256) { if (it >= 32) continue; type = 0; grp = 7; b = (it >> 2) & 7; hh = it & 3; }
;     ...
;                 else if (it < 384) { type = 1; samp = 1; b = (it - 256) >> 3; hh = it & 7; }
;                 else if (it < 448) { type = 2; samp = 1; b = (it - 384) >> 2; hh = it & 3; }
;                 else if (it < 512) { type = 0; samp = 1; b = (it - 448) >> 2; hh = it & 3; }
;                 else { const int q = it - 512, s = q % 96; qb = 7 - q / 96; if (s < 64) { type = 1; b = s >> 3; hh = s & 7; } else { type = 2; b = (s - 64) >> 2; hh = s & 3; } }
.Ldq_got:
	v_readfirstlane_b32 s2, v250
	s_movk_i32 s3, 0x1e0
	s_cmpk_lt_u32 s2, 0x1a0
	s_cselect_b32 s3, 0x60, s3
	s_cmpk_lt_u32 s2, 0xa0
	s_cselect_b32 s3, 0x2e0, s3
	s_add_i32 s2, s2, s3
	s_branch .Ldq_pub
.Ldq_atomic:
	s_add_u32 s6, s52, s34
	s_addc_u32 s7, s53, s35
	v_mov_b32_e32 v1, 1
	v_mov_b32_e32 v2, 0x3000
	global_atomic_add v1, v2, v1, s[6:7] offset:2112 sc0
	s_waitcnt vmcnt(0)
	v_readfirstlane_b32 s2, v1
	s_movk_i32 s3, 0x1e0
	s_cmpk_lt_u32 s2, 0x1a0
	s_cselect_b32 s3, 0x60, s3
	s_cmpk_lt_u32 s2, 0xa0
	s_cselect_b32 s3, 0x2e0, s3
	s_add_i32 s2, s2, s3
